# nt policy on last-use z loads in S5-nonfinal and V-transpose phase (protect q/k in MALL)
# speedup vs baseline: 1.0121x; 1.0017x over previous
.LBB0_259:
	v_mul_hi_i32 v4, v67, s18
	v_lshrrev_b32_e32 v5, 31, v4
	v_ashrrev_i32_e32 v4, 5, v4
	v_add_u32_e32 v14, v4, v5
	v_mul_lo_u32 v4, v14, s19
	v_sub_u32_e32 v32, v67, v4
	v_ashrrev_i32_e32 v62, 6, v14
	v_mov_b32_e32 v33, v189
	v_mov_b32_e32 v34, v189
	s_mov_b32 s0, s33
	v_cmp_lt_i32_e64 s[2:3], s20, v32
	v_cmp_gt_i32_e32 vcc, s21, v32
	v_lshlrev_b32_e32 v4, 6, v32
	v_ashrrev_i32_e32 v63, 31, v62
	s_and_saveexec_b64 s[0:1], vcc
	s_xor_b64 s[0:1], exec, s[0:1]
	v_lshlrev_b64 v[6:7], 13, v[62:63]
	v_ashrrev_i32_e32 v5, 31, v4
	v_lshl_add_u64 v[12:13], v[6:7], 0, v[4:5]
	s_andn2_saveexec_b64 s[0:1], s[0:1]
	v_lshlrev_b32_e32 v5, 8, v62
	v_add3_u32 v12, v4, v5, s22
	v_ashrrev_i32_e32 v13, 31, v12
	s_or_b64 exec, exec, s[0:1]
	global_load_dwordx2 v[28:29], v61, s[14:15] offset:32
	global_load_dwordx4 v[4:7], v61, s[14:15] offset:16
	global_load_dwordx4 v[8:11], v61, s[14:15]
	v_and_b32_e32 v66, 63, v14
	v_and_b32_e32 v64, 15, v34
	v_mov_b32_e32 v65, v61
	v_lshlrev_b32_e32 v60, 5, v66
	v_lshl_add_u64 v[12:13], v[12:13], 0, v[64:65]
	v_lshl_add_u64 v[14:15], s[60:61], 0, v[60:61]
	v_and_b32_e32 v60, 48, v34
	v_and_b32_e32 v75, 63, v34
	v_lshl_add_u64 v[14:15], v[14:15], 0, v[60:61]
	v_lshlrev_b64 v[12:13], 13, v[12:13]
	v_cmp_lt_u32_e64 s[0:1], 31, v75
	v_cmp_gt_u32_e64 s[6:7], 32, v75
	v_mov_b32_e32 v16, 0
	v_lshl_add_u64 v[30:31], v[14:15], 0, v[12:13]
	v_mov_b32_e32 v12, 0
	v_mov_b32_e32 v13, 0
	v_mov_b32_e32 v14, 0
	v_mov_b32_e32 v15, 0
	s_and_saveexec_b64 s[10:11], s[6:7]
	s_cbranch_execz .LBB0_265
	global_load_dwordx4 v[12:15], v[30:31], off nt
.LBB0_265:
	s_or_b64 exec, exec, s[10:11]
	v_mov_b32_e32 v17, 0
	v_mov_b32_e32 v18, 0
	v_mov_b32_e32 v19, 0
	s_and_saveexec_b64 s[10:11], s[6:7]
	s_cbranch_execz .LBB0_267
	v_add_co_u32_e32 v16, vcc, 0x20000, v30
	s_nop 1
	v_addc_co_u32_e32 v17, vcc, 0, v31, vcc
	global_load_dwordx4 v[16:19], v[16:17], off nt
.LBB0_267:
	s_or_b64 exec, exec, s[10:11]
	v_mov_b32_e32 v20, 0
	v_mov_b32_e32 v24, 0
	v_mov_b32_e32 v25, 0
	v_mov_b32_e32 v26, 0
	v_mov_b32_e32 v27, 0
	s_and_saveexec_b64 s[10:11], s[6:7]
	s_cbranch_execz .LBB0_269
	v_add_co_u32_e32 v22, vcc, 0x40000, v30
	s_nop 1
	v_addc_co_u32_e32 v23, vcc, 0, v31, vcc
	global_load_dwordx4 v[24:27], v[22:23], off nt
.LBB0_269:
	s_or_b64 exec, exec, s[10:11]
	v_mov_b32_e32 v21, 0
	v_mov_b32_e32 v22, 0
	v_mov_b32_e32 v23, 0
	s_and_saveexec_b64 s[10:11], s[6:7]
	s_cbranch_execz .LBB0_271
	v_add_co_u32_e32 v20, vcc, 0x60000, v30
	s_nop 1
	v_addc_co_u32_e32 v21, vcc, 0, v31, vcc
	global_load_dwordx4 v[20:23], v[20:21], off nt

.LBB0_292:
	v_ashrrev_i32_e32 v2, 4, v10
	v_mov_b32_e32 v50, v189
	v_mov_b32_e32 v0, v189
	v_ashrrev_i32_e32 v3, 31, v2
	v_lshlrev_b64 v[4:5], 6, v[2:3]
	v_bfe_u32 v11, v0, 3, 3
	v_or_b32_e32 v2, v4, v11
	v_mov_b32_e32 v3, v5
	v_and_b32_e32 v13, 15, v10
	v_lshlrev_b32_e32 v0, 3, v0
	v_lshlrev_b64 v[2:3], 13, v[2:3]
	v_and_b32_e32 v51, 56, v0
	v_lshl_add_u64 v[2:3], s[60:61], 0, v[2:3]
	v_lshlrev_b32_e32 v0, 7, v13
	v_lshl_add_u64 v[6:7], v[2:3], 0, v[0:1]
	v_lshlrev_b32_e32 v2, 1, v51
	v_mov_b32_e32 v3, v1
	v_lshl_add_u64 v[6:7], v[6:7], 0, v[2:3]
	v_add_co_u32_e32 v14, vcc, s5, v6
	v_or_b32_e32 v12, 8, v11
	s_nop 0
	v_addc_co_u32_e32 v15, vcc, 0, v7, vcc
	v_or_b32_e32 v6, v4, v12
	v_mov_b32_e32 v7, v5
	v_lshlrev_b64 v[6:7], 13, v[6:7]
	v_lshl_add_u64 v[6:7], s[60:61], 0, v[6:7]
	v_lshl_add_u64 v[6:7], v[6:7], 0, v[0:1]
	v_lshl_add_u64 v[6:7], v[6:7], 0, v[2:3]
	s_mov_b32 s10, s33
	v_add_co_u32_e32 v16, vcc, s5, v6
	v_mov_b32_e32 v19, v5
	s_nop 0
	v_addc_co_u32_e32 v17, vcc, 0, v7, vcc
	global_load_dwordx4 v[6:9], v[14:15], off offset:2048 nt
	global_load_dwordx4 v[22:25], v[16:17], off offset:2048 nt
	v_or_b32_e32 v14, 16, v11
	v_or_b32_e32 v16, v4, v14
	v_mov_b32_e32 v17, v5
	v_lshlrev_b64 v[16:17], 13, v[16:17]
	v_or_b32_e32 v15, 24, v11
	v_lshl_add_u64 v[16:17], s[60:61], 0, v[16:17]
	v_or_b32_e32 v18, v4, v15
	v_lshl_add_u64 v[16:17], v[16:17], 0, v[0:1]
	v_lshlrev_b64 v[18:19], 13, v[18:19]
	v_lshl_add_u64 v[16:17], v[16:17], 0, v[2:3]
	v_lshl_add_u64 v[18:19], s[60:61], 0, v[18:19]
	v_add_co_u32_e32 v16, vcc, s5, v16
	v_lshl_add_u64 v[18:19], v[18:19], 0, v[0:1]
	s_nop 0
	v_addc_co_u32_e32 v17, vcc, 0, v17, vcc
	v_lshl_add_u64 v[18:19], v[18:19], 0, v[2:3]
	v_add_co_u32_e32 v18, vcc, s5, v18
	v_mov_b32_e32 v21, v5
	s_nop 0
	v_addc_co_u32_e32 v19, vcc, 0, v19, vcc
	global_load_dwordx4 v[26:29], v[16:17], off offset:2048 nt
	global_load_dwordx4 v[30:33], v[18:19], off offset:2048 nt
	v_or_b32_e32 v16, 32, v11
	v_or_b32_e32 v18, v4, v16
	v_mov_b32_e32 v19, v5
	v_lshlrev_b64 v[18:19], 13, v[18:19]
	v_or_b32_e32 v17, 40, v11
	v_lshl_add_u64 v[18:19], s[60:61], 0, v[18:19]
	v_or_b32_e32 v20, v4, v17
	v_lshl_add_u64 v[18:19], v[18:19], 0, v[0:1]
	v_lshlrev_b64 v[20:21], 13, v[20:21]
	v_lshl_add_u64 v[18:19], v[18:19], 0, v[2:3]
	v_lshl_add_u64 v[20:21], s[60:61], 0, v[20:21]
	v_add_co_u32_e32 v18, vcc, s5, v18
	v_lshl_add_u64 v[20:21], v[20:21], 0, v[0:1]
	s_nop 0
	v_addc_co_u32_e32 v19, vcc, 0, v19, vcc
	v_lshl_add_u64 v[20:21], v[20:21], 0, v[2:3]
	v_add_co_u32_e32 v20, vcc, s5, v20
	s_nop 1
	v_addc_co_u32_e32 v21, vcc, 0, v21, vcc
	global_load_dwordx4 v[34:37], v[18:19], off offset:2048 nt
	global_load_dwordx4 v[38:41], v[20:21], off offset:2048 nt
	v_or_b32_e32 v18, 48, v11
	v_or_b32_e32 v20, v4, v18
	v_mov_b32_e32 v21, v5
	v_lshlrev_b64 v[20:21], 13, v[20:21]
	v_lshl_add_u64 v[20:21], s[60:61], 0, v[20:21]
	v_lshl_add_u64 v[20:21], v[20:21], 0, v[0:1]
	v_lshl_add_u64 v[20:21], v[20:21], 0, v[2:3]
	v_add_co_u32_e32 v20, vcc, s5, v20
	v_or_b32_e32 v19, 56, v11
	s_nop 0
	v_addc_co_u32_e32 v21, vcc, 0, v21, vcc
	global_load_dwordx4 v[42:45], v[20:21], off offset:2048 nt
	v_or_b32_e32 v20, v4, v19
	v_mov_b32_e32 v21, v5
	v_lshlrev_b64 v[20:21], 13, v[20:21]
	v_lshl_add_u64 v[20:21], s[60:61], 0, v[20:21]
	v_lshl_add_u64 v[20:21], v[20:21], 0, v[0:1]
	v_lshl_add_u64 v[20:21], v[20:21], 0, v[2:3]
	v_add_co_u32_e32 v20, vcc, s5, v20
	v_lshrrev_b32_e32 v0, 6, v50
	s_nop 0
	v_addc_co_u32_e32 v21, vcc, 0, v21, vcc
	global_load_dwordx4 v[46:49], v[20:21], off offset:2048 nt
	v_mul_lo_u32 v0, v0, s4
	v_add_u32_e32 v20, 0, v0
	v_mul_u32_u24_e32 v0, 0x48, v51
	v_lshlrev_b32_e32 v0, 1, v0
	v_lshlrev_b32_e32 v3, 1, v11
	v_add3_u32 v21, v20, v0, v3
	v_add3_u32 v0, v20, v3, v0
	s_waitcnt vmcnt(7)
	ds_write_b16 v21, v6
	ds_write_b16_d16_hi v0, v6 offset:144
	ds_write_b16 v21, v7 offset:288
	ds_write_b16_d16_hi v0, v7 offset:432
	ds_write_b16 v21, v8 offset:576
	ds_write_b16_d16_hi v0, v8 offset:720
	ds_write_b16 v21, v9 offset:864
	ds_write_b16_d16_hi v0, v9 offset:1008
	s_waitcnt vmcnt(6)
	ds_write_b16 v21, v22 offset:16
	ds_write_b16_d16_hi v0, v22 offset:160
	ds_write_b16 v21, v23 offset:304
	ds_write_b16_d16_hi v0, v23 offset:448
	ds_write_b16 v21, v24 offset:592
	ds_write_b16_d16_hi v0, v24 offset:736
	ds_write_b16 v21, v25 offset:880
	ds_write_b16_d16_hi v0, v25 offset:1024
	s_waitcnt vmcnt(5)
	ds_write_b16 v21, v26 offset:32
	ds_write_b16_d16_hi v0, v26 offset:176
	ds_write_b16 v21, v27 offset:320
	ds_write_b16_d16_hi v0, v27 offset:464
	ds_write_b16 v21, v28 offset:608
	ds_write_b16_d16_hi v0, v28 offset:752
	ds_write_b16 v21, v29 offset:896
	ds_write_b16_d16_hi v0, v29 offset:1040
	s_waitcnt vmcnt(4)
	ds_write_b16 v21, v30 offset:48
	ds_write_b16_d16_hi v0, v30 offset:192
	ds_write_b16 v21, v31 offset:336
	ds_write_b16_d16_hi v0, v31 offset:480
	ds_write_b16 v21, v32 offset:624
	ds_write_b16_d16_hi v0, v32 offset:768
	ds_write_b16 v21, v33 offset:912
	ds_write_b16_d16_hi v0, v33 offset:1056
	s_waitcnt vmcnt(3)
	ds_write_b16 v21, v34 offset:64
	ds_write_b16_d16_hi v0, v34 offset:208
	ds_write_b16 v21, v35 offset:352
	ds_write_b16_d16_hi v0, v35 offset:496
	ds_write_b16 v21, v36 offset:640
	ds_write_b16_d16_hi v0, v36 offset:784
	ds_write_b16 v21, v37 offset:928
	ds_write_b16_d16_hi v0, v37 offset:1072
	s_waitcnt vmcnt(2)
	ds_write_b16 v21, v38 offset:80
	ds_write_b16_d16_hi v0, v38 offset:224
	ds_write_b16 v21, v39 offset:368
	ds_write_b16_d16_hi v0, v39 offset:512
	ds_write_b16 v21, v40 offset:656
	ds_write_b16_d16_hi v0, v40 offset:800
	ds_write_b16 v21, v41 offset:944
	ds_write_b16_d16_hi v0, v41 offset:1088
	s_waitcnt vmcnt(1)
	ds_write_b16 v21, v42 offset:96
	ds_write_b16_d16_hi v0, v42 offset:240
	ds_write_b16 v21, v43 offset:384
	ds_write_b16_d16_hi v0, v43 offset:528
	ds_write_b16 v21, v44 offset:672
	ds_write_b16_d16_hi v0, v44 offset:816
	ds_write_b16 v21, v45 offset:960
	ds_write_b16_d16_hi v0, v45 offset:1104
	s_waitcnt vmcnt(0)
	ds_write_b16 v21, v46 offset:112
	ds_write_b16_d16_hi v0, v46 offset:256
	ds_write_b16 v21, v47 offset:400
	ds_write_b16_d16_hi v0, v47 offset:544
	ds_write_b16 v21, v48 offset:688
	ds_write_b16_d16_hi v0, v48 offset:832
	ds_write_b16 v21, v49 offset:976
	ds_write_b16_d16_hi v0, v49 offset:1120
	s_waitcnt lgkmcnt(0)
	v_cmp_lt_u64_e32 vcc, s[8:9], v[4:5]
	s_and_saveexec_b64 s[10:11], vcc
	s_xor_b64 s[10:11], exec, s[10:11]
	v_add_u32_e32 v0, 0xffff8000, v4
	v_ashrrev_i32_e32 v0, 4, v0
	v_and_b32_e32 v3, 0xc0, v4
	v_and_or_b32 v4, v0, -16, v13
	v_ashrrev_i32_e32 v5, 31, v4
	v_lshlrev_b64 v[4:5], 15, v[4:5]
	v_lshl_add_u64 v[4:5], s[46:47], 0, v[4:5]
	v_lshlrev_b32_e32 v0, 1, v3
	v_lshl_add_u64 v[8:9], v[4:5], 0, v[0:1]
	s_or_saveexec_b64 s[10:11], s[10:11]
	v_mov_b64_e32 v[6:7], 0x100
	s_xor_b64 exec, exec, s[10:11]
	s_cbranch_execz .LBB0_291
	v_lshrrev_b32_e32 v0, 9, v4
	v_and_or_b32 v0, v0, 48, v13
	v_and_b32_e32 v3, 0x1fc0, v4
	v_lshlrev_b32_e32 v0, 20, v0
	v_lshl_add_u64 v[4:5], s[2:3], 0, v[0:1]
	v_lshlrev_b32_e32 v0, 1, v3
	v_lshl_add_u64 v[8:9], v[4:5], 0, v[0:1]
	v_mov_b64_e32 v[6:7], 0x2000
	s_branch .LBB0_291
